# S5A/S5C grouped GEMMs: units remapped so each XCD owns 4 groups (B tile read into one L2 instead of eight) (run 1)
# baseline (speedup 1.0000x reference)
;     __device__ bool next(int i, Unit& u) const { if (r0 + i >= r1) return false; return base.next(r0 + i, u); }
;     __device__ bool next(int i, Unit& u) const { const int L = i * G + c; if (L >= 256) return false; u.pm = L; u.pn = L >> 3; return true; }
; #define PG8_WAIT_V(n) asm volatile("s_waitcnt vmcnt(" #n ")" ::: "memory")
; #define PG8_BAR __builtin_amdgcn_s_barrier()
; #define lane lane_id()
; template <class Epi, class Sched>
; __device__ __forceinline__ void gemm_phase(LAS unsigned char* lds, const Gemm g, const Sched& S, const Epi& E, int wave_id) {
;     ...
;     const int wid = wave_id, lane = tid & 63, wr = wid >> 2, wc = wid & 3, fr = lane & 15, fq = lane >> 4;
;     const int K = g.K, nt = K / BK;
;     unsigned voffA[2], voffB[2];
; #pragma unroll
;     for (int i = 0; i < 2; ++i) { int R, C; stage_rc(tid * 16 + i * 8192, R, C); const int Rb = (R & ~31) + perm32(R & 31);
;         voffA[i] = (unsigned)(R * g.lda + C) * 2u; voffB[i] = (unsigned)(Rb * g.ldb + C) * 2u; }
;     const size_t kstep = (size_t)(BK * 2);
;     const size_t hstepA = (size_t)HALF * g.lda * 2, hstepB = (size_t)HALF * g.ldb * 2;
;     const size_t tstepA = 2 * hstepA, tstepB = 2 * hstepB;
;     const unsigned ldsw = (unsigned)wid * 1024u;
;     const int aoff = lds_byte(wr * 64 + fr, fq * 8), boff = lds_byte(wc * 32 + fr, fq * 8);
;     ...
;     Unit cur, nxt; int ui = 0;
;     if (!S.next(0, cur)) return;
;     f32x4 acc[2][2][4][2];
; #pragma unroll
;     for (int a = 0; a < 2; ++a)
; #pragma unroll
;         for (int b = 0; b < 2; ++b)
; #pragma unroll
;             for (int m = 0; m < 4; ++m)
; #pragma unroll
;                 for (int n = 0; n < 2; ++n) acc[a][b][m][n] = (f32x4){0.f, 0.f, 0.f, 0.f};
;     bf16x8 At[4][2], B0[2][2], B1[2][2];
;     const char* cA = (const char*)g.A + (size_t)cur.pm * tstepA; const char* cB = (const char*)g.Bt + (size_t)cur.pn * tstepB;
;     PG8_STAGE(PG8_SB(0, 0), cB, voffB); PG8_STAGE(PG8_SB(0, 1), cB + hstepB, voffB); PG8_STAGE(PG8_SA(0, 0), cA, voffA); PG8_STAGE(PG8_SA(0, 1), cA + hstepA, voffA);
;     if (wr == 1) PG8_BAR;
;     PG8_WAIT_V(2); PG8_BAR;
;     PG8_STAGE(PG8_SB(1, 0), cB + kstep, voffB); PG8_STAGE(PG8_SA(1, 0), cA + kstep, voffA); PG8_STAGE(PG8_SB(1, 1), cB + hstepB + kstep, voffB);
;     PG8_WAIT_V(6); PG8_BAR;
.LBB0_685:
	v_readlane_b32 s2, v255, 9
	v_mbcnt_lo_u32_b32 v0, -1, 0
	v_mbcnt_hi_u32_b32 v0, -1, v0
	s_lshr_b32 s49, s80, 8
	s_lshl_b32 s44, s97, 10
	v_add_u32_e32 v8, s2, v0
	s_lshl_b32 s2, s97, 5
	s_and_b32 s53, s2, 0x60
	s_lshl_b32 s55, s49, 6
	s_lshl_b32 s54, s49, 13
	s_lshl_b32 s52, s53, 7
	s_cmpk_gt_i32 s66, 0xff
	s_cbranch_scc1 .LBB0_709
	s_and_b32 s98, s66, 7
	s_lshl_b32 s98, s98, 5
	s_lshr_b32 s99, s66, 3
	s_or_b32 s98, s98, s99
	v_lshlrev_b32_e32 v0, 4, v8
	v_add_u32_e32 v1, 0x2000, v0
	v_ashrrev_i32_e32 v2, 31, v1
	v_lshrrev_b32_e32 v2, 22, v2
	v_add_u32_e32 v2, v1, v2
	v_ashrrev_i32_e32 v2, 10, v2
	v_mul_i32_i24_e32 v3, 0x400, v2
	v_sub_u32_e32 v1, v1, v3
	v_lshrrev_b32_e32 v3, 4, v1
	v_bitop3_b32 v1, v3, v1, 32 bitop3:0x6c
	v_ashrrev_i32_e32 v3, 31, v1
	v_lshrrev_b32_e32 v3, 26, v3
	v_add_u32_e32 v3, v1, v3
	v_lshlrev_b32_e32 v5, 3, v2
	v_ashrrev_i32_e32 v4, 6, v3
	v_and_b32_e32 v5, -16, v5
	v_and_b32_e32 v3, 0xc0, v3
	v_add_u32_e32 v5, v4, v5
	v_lshlrev_b32_e32 v2, 5, v2
	v_sub_u32_e32 v1, v1, v3
	v_mov_b32_e32 v3, 1
	v_and_b32_e32 v4, 3, v4
	s_mov_b32 s5, 0x7fffe0
	v_lshrrev_b32_e32 v6, 2, v5
	v_lshlrev_b32_e32 v7, 1, v5
	v_and_b32_e32 v2, 32, v2
	v_ashrrev_i16_sdwa v1, v3, sext(v1) dst_sel:DWORD dst_unused:UNUSED_PAD src0_sel:DWORD src1_sel:BYTE_0
	v_and_or_b32 v4, v5, s5, v4
	v_and_b32_e32 v6, 4, v6
	v_and_b32_e32 v7, 24, v7
	v_add_u32_sdwa v1, v2, sext(v1) dst_sel:DWORD dst_unused:UNUSED_PAD src0_sel:DWORD src1_sel:WORD_0
	v_or3_b32 v4, v4, v6, v7
	v_lshlrev_b32_e32 v2, 1, v1
	s_movk_i32 s6, 0x180
	v_lshl_add_u32 v64, v4, 9, v2
	v_mul_lo_u32 v2, v5, s6
	v_add_lshl_u32 v66, v1, v2, 1
	v_bfe_i32 v1, v8, 27, 1
	v_lshrrev_b32_e32 v1, 22, v1
	v_add_u32_e32 v1, v0, v1
	v_and_b32_e32 v1, 0xfffffc00, v1
	v_sub_u32_e32 v0, v0, v1
	v_lshrrev_b32_e32 v1, 4, v0
	v_ashrrev_i32_e32 v4, 31, v8
	v_bitop3_b32 v0, v1, v0, 32 bitop3:0x6c
	v_lshrrev_b32_e32 v4, 26, v4
	v_ashrrev_i32_e32 v1, 31, v0
	v_add_u32_e32 v4, v8, v4
	v_lshrrev_b32_e32 v1, 26, v1
	v_ashrrev_i32_e32 v4, 6, v4
	v_add_u32_e32 v1, v0, v1
	v_lshlrev_b32_e32 v5, 3, v4
	s_add_u32 s2, s92, 0x1d00000
	v_ashrrev_i32_e32 v2, 6, v1
	v_and_b32_e32 v5, -16, v5
	s_addc_u32 s33, s93, 0
	s_ashr_i32 s4, s98, 3
	v_add_u32_e32 v5, v2, v5
	v_and_b32_e32 v2, 3, v2
	v_and_b32_e32 v1, 0xc0, v1
	v_and_or_b32 v2, v5, s5, v2
	v_lshlrev_b32_e32 v4, 5, v4
	v_sub_u32_e32 v0, v0, v1
	s_ashr_i32 s5, s4, 31
	v_lshrrev_b32_e32 v6, 2, v5
	v_lshlrev_b32_e32 v7, 1, v5
	v_and_b32_e32 v4, 32, v4
	v_ashrrev_i16_sdwa v0, v3, sext(v0) dst_sel:DWORD dst_unused:UNUSED_PAD src0_sel:DWORD src1_sel:BYTE_0
	s_lshl_b64 s[4:5], s[4:5], 17
	v_and_b32_e32 v6, 4, v6
	v_and_b32_e32 v7, 24, v7
	v_add_u32_sdwa v0, v4, sext(v0) dst_sel:DWORD dst_unused:UNUSED_PAD src0_sel:DWORD src1_sel:WORD_0
	s_add_u32 s30, s2, s4
	v_or3_b32 v2, v2, v6, v7
	v_lshlrev_b32_e32 v1, 1, v0
	s_addc_u32 s31, s33, s5
	s_add_i32 s36, s44, 0
	v_lshl_add_u32 v68, v2, 9, v1
	s_add_i32 m0, s36, 0x10000
	s_mul_i32 s7, s98, 0x30000
	global_load_lds_dwordx4 v68, s[30:31]
	s_add_i32 m0, s36, 0x12000
	s_add_u32 s4, s30, 0x10000
	s_addc_u32 s5, s31, 0
	s_add_i32 s37, s36, 0x14000
	global_load_lds_dwordx4 v64, s[30:31]
	s_mov_b32 m0, s37
	s_add_i32 s38, s36, 0x16000
	global_load_lds_dwordx4 v68, s[4:5]
	s_mov_b32 m0, s38
	v_mul_lo_u32 v1, v5, s6
	s_mul_hi_i32 s6, s98, 0x30000
	global_load_lds_dwordx4 v64, s[4:5]
	s_add_u32 s4, s92, s7
	s_addc_u32 s5, s93, s6
	s_add_u32 s28, s4, 0x17400000
	s_addc_u32 s29, s5, 0
	s_add_i32 s39, s36, 0x2000
	v_add_lshl_u32 v70, v0, v1, 1
	s_mov_b32 m0, s36
	s_add_u32 s4, s4, 0x17418000
	global_load_lds_dwordx4 v70, s[28:29]
	s_mov_b32 m0, s39
	s_addc_u32 s5, s5, 0
	s_add_i32 s45, s36, 0x4000
	global_load_lds_dwordx4 v66, s[28:29]
	s_mov_b32 m0, s45
	s_add_i32 s46, s36, 0x6000
	global_load_lds_dwordx4 v70, s[4:5]
	s_mov_b32 m0, s46
	v_mov_b32_e32 v69, 0
	global_load_lds_dwordx4 v66, s[4:5]
	v_mov_b32_e32 v65, v69
	v_mov_b32_e32 v71, v69
	v_mov_b32_e32 v67, v69
	s_cmp_eq_u32 s49, 1
	s_mov_b32 s47, 0
	v_lshl_add_u64 v[6:7], s[30:31], 0, v[68:69]
	v_lshl_add_u64 v[2:3], s[30:31], 0, v[64:65]
	s_mov_b64 s[6:7], 0x10000
	v_lshl_add_u64 v[0:1], s[28:29], 0, v[70:71]
	s_cselect_b64 s[8:9], -1, 0
	s_cmp_lg_u32 s49, 1
	v_lshl_add_u64 v[4:5], s[28:29], 0, v[66:67]
	s_cbranch_scc1 .LBB0_688
	s_barrier
.LBB0_688:
	s_mov_b64 s[10:11], 0x80
	s_add_i32 m0, s36, 0x18000
	v_lshl_add_u64 v[6:7], v[6:7], 0, s[10:11]
	s_waitcnt vmcnt(2)
	s_barrier
	global_load_lds_dwordx4 v[6:7], off
	v_lshl_add_u64 v[2:3], v[2:3], 0, s[10:11]
	s_add_i32 m0, s36, 0x1a000
	s_add_i32 s48, s36, 0x8000
	s_add_i32 s50, s36, 0xa000
	global_load_lds_dwordx4 v[2:3], off
	v_lshl_add_u64 v[0:1], v[0:1], 0, s[10:11]
	s_mov_b32 m0, s48
	s_add_u32 s4, s30, 0x10080
	global_load_lds_dwordx4 v[0:1], off
	v_lshl_add_u64 v[0:1], v[4:5], 0, s[10:11]
	s_mov_b32 m0, s50
	s_addc_u32 s5, s31, 0
	s_add_i32 s51, s36, 0x1c000
	global_load_lds_dwordx4 v[0:1], off
	s_mov_b32 m0, s51
	s_add_i32 s58, s36, 0x1e000
	global_load_lds_dwordx4 v68, s[4:5]
	v_lshl_add_u64 v[0:1], s[4:5], 0, v[64:65]
	s_mov_b32 m0, s58
	s_movk_i32 s4, 0x3c0
	global_load_lds_dwordx4 v[0:1], off
	v_and_b32_e32 v0, 15, v8
	v_lshrrev_b32_e32 v1, 1, v8
	v_or_b32_e32 v74, s55, v0
	v_and_b32_e32 v1, 24, v1
	v_lshlrev_b32_e32 v2, 6, v74
	v_lshlrev_b32_e32 v3, 1, v1
	v_and_or_b32 v2, v2, s4, v3
	v_lshl_or_b32 v0, v0, 6, v3
	v_lshlrev_b32_e32 v3, 2, v8
	v_and_b32_e32 v3, 32, v3
	v_bitop3_b32 v3, v0, s52, v3 bitop3:0xde
	v_or_b32_e32 v0, s53, v1
	s_cmpk_lt_u32 s80, 0x100
	v_lshlrev_b32_e32 v0, 2, v0
	v_mov_b32_e32 v1, v69
	v_readlane_b32 s16, v255, 1
	s_cselect_b64 s[4:5], -1, 0
	v_lshl_add_u64 v[0:1], s[92:93], 0, v[0:1]
	s_mov_b64 s[12:13], 0x1d400000
	s_add_i32 s59, s66, s16
	v_lshl_add_u64 v[72:73], v[0:1], 0, s[12:13]
	s_mul_i32 s13, s59, 0x30000
	s_mul_hi_i32 s12, s59, 0x30000
	s_add_u32 s13, s92, s13
	s_addc_u32 s14, s93, s12
	v_lshlrev_b32_e32 v4, 2, v74
	s_add_u32 s12, s13, 0x17400000
	v_and_b32_e32 v4, 32, v4
	s_waitcnt vmcnt(6)
	s_addc_u32 s13, s14, 0
	s_add_i32 s64, 0, 0x10000
	s_mov_b32 s22, s98
	s_add_i32 s66, 0, 0x18000
	v_bitop3_b32 v2, v2, s54, v4 bitop3:0xde
	v_readlane_b32 s17, v255, 2
	v_add_u32_e32 v75, s64, v3
	s_add_i32 s64, s64, s44
	v_cndmask_b32_e64 v0, 0, 1, s[4:5]
	v_add_u32_e32 v77, s66, v3
	s_add_i32 s66, s66, s44
	s_mul_hi_i32 s60, s16, 0x30000
	s_mul_i32 s61, s16, 0x30000
	v_add_u32_e32 v76, 0, v2
	s_add_i32 s62, s36, 0xc000
	s_add_i32 s63, s36, 0xe000
	s_mov_b64 s[14:15], 0x100
	s_add_i32 s65, s64, 0x2000
	s_mov_b64 s[16:17], 0x180
	s_add_i32 s67, s66, 0x2000
	v_cmp_ne_u32_e64 s[4:5], 1, v0
	s_mov_b32 s73, s22
	s_mov_b64 s[22:23], s[28:29]
	s_barrier
	s_branch .LBB0_691

;     __device__ bool next(int i, Unit& u) const { if (r0 + i >= r1) return false; return base.next(r0 + i, u); }
;     __device__ bool next(int i, Unit& u) const { const int L = i * G + c; if (L >= 256) return false; u.pm = L; u.pn = L >> 3; return true; }
; #define PG8_STAGE(bufoff, gbase, voff) do { _Pragma("unroll") for (int _i = 0; _i < 2; ++_i) \
;         __builtin_amdgcn_global_load_lds((const unsigned*)((const char*)(gbase) + (voff)[_i]), (LAS unsigned*)(lds + (bufoff) + ldsw + _i * 8192), 16, 0, 0); } while (0)
; #define lane lane_id()
; template <class Epi, class Sched>
; __device__ __forceinline__ void gemm_phase(LAS unsigned char* lds, const Gemm g, const Sched& S, const Epi& E, int wave_id) {
;     ...
;     const int wid = wave_id, lane = tid & 63, wr = wid >> 2, wc = wid & 3, fr = lane & 15, fq = lane >> 4;
;     const int K = g.K, nt = K / BK;
;     unsigned voffA[2], voffB[2];
; #pragma unroll
;     for (int i = 0; i < 2; ++i) { int R, C; stage_rc(tid * 16 + i * 8192, R, C); const int Rb = (R & ~31) + perm32(R & 31);
;         voffA[i] = (unsigned)(R * g.lda + C) * 2u; voffB[i] = (unsigned)(Rb * g.ldb + C) * 2u; }
;     const size_t kstep = (size_t)(BK * 2);
;     const size_t hstepA = (size_t)HALF * g.lda * 2, hstepB = (size_t)HALF * g.ldb * 2;
;     const size_t tstepA = 2 * hstepA, tstepB = 2 * hstepB;
;     const unsigned ldsw = (unsigned)wid * 1024u;
;     const int aoff = lds_byte(wr * 64 + fr, fq * 8), boff = lds_byte(wc * 32 + fr, fq * 8);
;     ...
;     Unit cur, nxt; int ui = 0;
;     if (!S.next(0, cur)) return;
;     f32x4 acc[2][2][4][2];
; #pragma unroll
;     for (int a = 0; a < 2; ++a)
; #pragma unroll
;         for (int b = 0; b < 2; ++b)
; #pragma unroll
;             for (int m = 0; m < 4; ++m)
; #pragma unroll
;                 for (int n = 0; n < 2; ++n) acc[a][b][m][n] = (f32x4){0.f, 0.f, 0.f, 0.f};
;     bf16x8 At[4][2], B0[2][2], B1[2][2];
;     const char* cA = (const char*)g.A + (size_t)cur.pm * tstepA; const char* cB = (const char*)g.Bt + (size_t)cur.pn * tstepB;
;     PG8_STAGE(PG8_SB(0, 0), cB, voffB); PG8_STAGE(PG8_SB(0, 1), cB + hstepB, voffB); PG8_STAGE(PG8_SA(0, 0), cA, voffA); PG8_STAGE(PG8_SA(0, 1), cA + hstepA, voffA);
.LBB0_926:
	v_readlane_b32 s8, v255, 3
	s_cmp_lt_i32 s8, 5
	v_readlane_b32 s9, v255, 4
	s_cselect_b64 s[2:3], -1, 0
	s_and_b64 s[8:9], s[2:3], s[4:5]
	s_andn2_b64 vcc, exec, s[8:9]
	v_readlane_b32 s10, v255, 5
	v_readlane_b32 s11, v255, 6
	s_cbranch_vccnz .LBB0_967
	v_readlane_b32 s2, v255, 9
	s_lshr_b32 s3, s80, 8
	v_mbcnt_lo_u32_b32 v0, -1, 0
	v_mbcnt_hi_u32_b32 v0, -1, v0
	s_lshl_b32 s33, s3, 13
	v_add_u32_e32 v8, s2, v0
	s_lshl_b32 s2, s97, 10
	s_cmpk_gt_i32 s66, 0xff
	s_cbranch_scc1 .LBB0_943
	s_and_b32 s98, s66, 7
	s_lshl_b32 s98, s98, 5
	s_lshr_b32 s99, s66, 3
	s_or_b32 s98, s98, s99
	v_lshlrev_b32_e32 v0, 4, v8
	v_add_u32_e32 v1, 0x2000, v0
	v_ashrrev_i32_e32 v2, 31, v1
	v_lshrrev_b32_e32 v2, 22, v2
	v_add_u32_e32 v2, v1, v2
	v_ashrrev_i32_e32 v2, 10, v2
	v_mul_i32_i24_e32 v3, 0x400, v2
	v_sub_u32_e32 v1, v1, v3
	v_lshrrev_b32_e32 v3, 4, v1
	v_bitop3_b32 v1, v3, v1, 32 bitop3:0x6c
	v_ashrrev_i32_e32 v3, 31, v1
	v_lshrrev_b32_e32 v3, 26, v3
	v_add_u32_e32 v3, v1, v3
	v_lshlrev_b32_e32 v5, 3, v2
	v_ashrrev_i32_e32 v4, 6, v3
	v_and_b32_e32 v5, -16, v5
	v_add_u32_e32 v5, v4, v5
	v_and_b32_e32 v4, 3, v4
	s_mov_b32 s4, 0x1ffffe0
	v_lshrrev_b32_e32 v6, 2, v5
	v_lshlrev_b32_e32 v7, 1, v5
	v_and_b32_e32 v3, 0xc0, v3
	v_and_or_b32 v4, v5, s4, v4
	v_and_b32_e32 v6, 4, v6
	v_and_b32_e32 v7, 24, v7
	v_lshlrev_b32_e32 v2, 5, v2
	v_sub_u32_e32 v1, v1, v3
	v_mov_b32_e32 v3, 1
	v_or3_b32 v4, v4, v6, v7
	s_movk_i32 s5, 0x180
	v_and_b32_e32 v2, 32, v2
	v_ashrrev_i16_sdwa v1, v3, sext(v1) dst_sel:DWORD dst_unused:UNUSED_PAD src0_sel:DWORD src1_sel:BYTE_0
	v_mul_lo_u32 v4, v4, s5
	v_add_u32_sdwa v1, v2, sext(v1) dst_sel:DWORD dst_unused:UNUSED_PAD src0_sel:DWORD src1_sel:WORD_0
	v_mul_lo_u32 v2, v5, s5
	v_add_lshl_u32 v128, v4, v1, 1
	v_add_lshl_u32 v130, v1, v2, 1
	v_bfe_i32 v1, v8, 27, 1
	v_lshrrev_b32_e32 v1, 22, v1
	v_add_u32_e32 v1, v0, v1
	v_and_b32_e32 v1, 0xfffffc00, v1
	v_sub_u32_e32 v0, v0, v1
	v_lshrrev_b32_e32 v1, 4, v0
	v_ashrrev_i32_e32 v4, 31, v8
	v_bitop3_b32 v0, v1, v0, 32 bitop3:0x6c
	v_lshrrev_b32_e32 v4, 26, v4
	v_ashrrev_i32_e32 v1, 31, v0
	v_add_u32_e32 v4, v8, v4
	v_lshrrev_b32_e32 v1, 26, v1
	v_ashrrev_i32_e32 v4, 6, v4
	v_add_u32_e32 v1, v0, v1
	v_lshlrev_b32_e32 v5, 3, v4
	v_ashrrev_i32_e32 v2, 6, v1
	v_and_b32_e32 v5, -16, v5
	v_add_u32_e32 v5, v2, v5
	v_and_b32_e32 v2, 3, v2
	v_lshrrev_b32_e32 v6, 2, v5
	v_lshlrev_b32_e32 v7, 1, v5
	s_add_u32 s36, s92, 0x1700000
	v_and_or_b32 v2, v5, s4, v2
	v_and_b32_e32 v6, 4, v6
	v_and_b32_e32 v7, 24, v7
	s_addc_u32 s37, s93, 0
	s_ashr_i32 s61, s98, 3
	v_or3_b32 v2, v2, v6, v7
	v_and_b32_e32 v1, 0xc0, v1
	v_mul_lo_u32 v2, v2, s5
	v_lshlrev_b32_e32 v4, 5, v4
	v_sub_u32_e32 v0, v0, v1
	v_mul_lo_u32 v1, v5, s5
	s_mul_i32 s5, s61, 0x30000
	v_and_b32_e32 v4, 32, v4
	v_ashrrev_i16_sdwa v0, v3, sext(v0) dst_sel:DWORD dst_unused:UNUSED_PAD src0_sel:DWORD src1_sel:BYTE_0
	s_mul_hi_i32 s4, s61, 0x30000
	s_add_u32 s34, s36, s5
	v_add_u32_sdwa v0, v4, sext(v0) dst_sel:DWORD dst_unused:UNUSED_PAD src0_sel:DWORD src1_sel:WORD_0
	s_addc_u32 s35, s37, s4
	s_add_i32 s38, s2, 0
	v_add_lshl_u32 v132, v2, v0, 1
	s_add_i32 m0, s38, 0x10000
	s_mul_i32 s7, s98, 0x30000
	global_load_lds_dwordx4 v132, s[34:35]
	s_add_i32 m0, s38, 0x12000
	s_add_u32 s4, s34, 0x18000
	global_load_lds_dwordx4 v128, s[34:35]
	s_addc_u32 s5, s35, 0
	s_add_i32 m0, s38, 0x14000
	s_mul_hi_i32 s6, s98, 0x30000
	global_load_lds_dwordx4 v132, s[4:5]
	s_add_i32 m0, s38, 0x16000
	v_add_lshl_u32 v134, v0, v1, 1
	global_load_lds_dwordx4 v128, s[4:5]
	s_add_u32 s4, s92, s7
	s_addc_u32 s5, s93, s6
	s_add_u32 s30, s4, 0x17400000
	s_addc_u32 s31, s5, 0
	s_add_i32 s39, s38, 0x2000
	s_mov_b32 m0, s38
	s_add_u32 s4, s4, 0x17418000
	global_load_lds_dwordx4 v134, s[30:31]
	s_mov_b32 m0, s39
	s_addc_u32 s5, s5, 0
	s_add_i32 s40, s38, 0x4000
	global_load_lds_dwordx4 v130, s[30:31]
	s_mov_b32 m0, s40
	s_add_i32 s41, s38, 0x6000
	global_load_lds_dwordx4 v134, s[4:5]
	s_mov_b32 m0, s41
	v_mov_b32_e32 v137, 0
	global_load_lds_dwordx4 v130, s[4:5]
	v_mov_b32_e32 v133, v137
	v_mov_b32_e32 v129, v137
	v_mov_b32_e32 v135, v137
	v_mov_b32_e32 v131, v137
	s_cmp_eq_u32 s3, 1
	s_mov_b32 s42, 0
	v_lshl_add_u64 v[6:7], s[34:35], 0, v[132:133]
	v_lshl_add_u64 v[4:5], s[34:35], 0, v[128:129]
	v_lshl_add_u64 v[0:1], s[30:31], 0, v[134:135]
	s_cselect_b64 s[10:11], -1, 0
	s_cmp_lg_u32 s3, 1
	v_lshl_add_u64 v[2:3], s[30:31], 0, v[130:131]
	s_cbranch_scc1 .LBB0_930
	s_barrier
;     __device__ bool next(int i, Unit& u) const { if (r0 + i >= r1) return false; return base.next(r0 + i, u); }
;     __device__ bool next(int i, Unit& u) const { const int L = i * G + c; if (L >= 256) return false; u.pm = L; u.pn = L >> 3; return true; }
; #define PG8_STAGE(bufoff, gbase, voff) do { _Pragma("unroll") for (int _i = 0; _i < 2; ++_i) \
;         __builtin_amdgcn_global_load_lds((const unsigned*)((const char*)(gbase) + (voff)[_i]), (LAS unsigned*)(lds + (bufoff) + ldsw + _i * 8192), 16, 0, 0); } while (0)
; #define PG8_WAIT_V(n) asm volatile("s_waitcnt vmcnt(" #n ")" ::: "memory")
; #define PG8_BAR __builtin_amdgcn_s_barrier()
; template <class Epi, class Sched>
; __device__ __forceinline__ void gemm_phase(LAS unsigned char* lds, const Gemm g, const Sched& S, const Epi& E, int wave_id) {
;     ...
;     PG8_STAGE(PG8_SB(0, 0), cB, voffB); PG8_STAGE(PG8_SB(0, 1), cB + hstepB, voffB); PG8_STAGE(PG8_SA(0, 0), cA, voffA); PG8_STAGE(PG8_SA(0, 1), cA + hstepA, voffA);
;     if (wr == 1) PG8_BAR;
;     PG8_WAIT_V(2); PG8_BAR;
;     PG8_STAGE(PG8_SB(1, 0), cB + kstep, voffB); PG8_STAGE(PG8_SA(1, 0), cA + kstep, voffA); PG8_STAGE(PG8_SB(1, 1), cB + hstepB + kstep, voffB);
;     PG8_WAIT_V(6); PG8_BAR;
;     for (;;) {
;         const bool has_next = S.next(ui + 1, nxt);
;         const char* nA = has_next ? (const char*)g.A + (size_t)nxt.pm * tstepA : cA; const char* nB = has_next ? (const char*)g.Bt + (size_t)nxt.pn * tstepB : cB;
.LBB0_930:
	s_lshl_b32 s4, s97, 5
	s_mov_b64 s[12:13], 0x80
	s_and_b32 s6, s4, 0x60
	s_add_i32 m0, s38, 0x18000
	v_lshl_add_u64 v[6:7], v[6:7], 0, s[12:13]
	s_lshl_b32 s7, s6, 7
	s_waitcnt vmcnt(2)
	s_barrier
	global_load_lds_dwordx4 v[6:7], off
	v_lshl_add_u64 v[4:5], v[4:5], 0, s[12:13]
	s_add_i32 m0, s38, 0x1a000
	s_add_i32 s43, s38, 0x8000
	s_add_i32 s44, s38, 0xa000
	global_load_lds_dwordx4 v[4:5], off
	v_lshl_add_u64 v[0:1], v[0:1], 0, s[12:13]
	s_mov_b32 m0, s43
	s_add_u32 s4, s34, 0x18080
	global_load_lds_dwordx4 v[0:1], off
	v_lshl_add_u64 v[0:1], v[2:3], 0, s[12:13]
	s_mov_b32 m0, s44
	s_addc_u32 s5, s35, 0
	global_load_lds_dwordx4 v[0:1], off
	s_add_i32 m0, s38, 0x1c000
	s_nop 0
	global_load_lds_dwordx4 v132, s[4:5]
	v_lshl_add_u64 v[0:1], s[4:5], 0, v[128:129]
	s_add_i32 m0, s38, 0x1e000
	s_cmpk_lt_u32 s80, 0x100
	global_load_lds_dwordx4 v[0:1], off
	v_and_b32_e32 v1, 15, v8
	v_lshrrev_b32_e32 v0, 1, v8
	v_and_b32_e32 v2, 24, v0
	v_lshlrev_b32_e32 v3, 6, v1
	v_lshl_or_b32 v3, v2, 1, v3
	s_cselect_b64 s[4:5], -1, 0
	v_or_b32_e32 v2, s6, v2
	s_lshl_b32 s6, s3, 10
	v_lshlrev_b32_e32 v4, 2, v8
	s_add_u32 s14, s92, 0x1c400000
	v_readlane_b32 s18, v255, 1
	v_and_b32_e32 v4, 32, v4
	s_addc_u32 s15, s93, 0
	s_add_i32 s45, s66, s18
	v_bitop3_b32 v5, v3, s33, v4 bitop3:0xde
	v_bitop3_b32 v3, v3, s7, v4 bitop3:0xde
	v_lshrrev_b32_e32 v2, 4, v2
	v_lshlrev_b32_e32 v1, 4, v1
	s_mul_i32 s7, s45, 0x30000
	v_or3_b32 v139, v1, s6, v2
	s_mul_hi_i32 s6, s45, 0x30000
	s_add_u32 s7, s92, s7
	s_addc_u32 s6, s93, s6
	s_add_u32 s16, s7, 0x17400000
	s_waitcnt vmcnt(6)
	s_addc_u32 s17, s6, 0
	s_add_i32 s50, 0, 0x10000
	s_add_i32 s52, 0, 0x14000
	s_add_i32 s54, 0, 0x18000
	s_add_i32 s58, 0, 0x1c000
	v_and_b32_e32 v0, 8, v0
	v_readlane_b32 s19, v255, 2
	v_add_u32_e32 v147, s50, v3
	v_add_u32_e32 v148, s52, v3
	v_cndmask_b32_e64 v1, 0, 1, s[4:5]
	s_add_i32 s50, s50, s2
	s_add_i32 s52, s52, s2
	v_add_u32_e32 v149, s54, v3
	v_add_u32_e32 v150, s58, v3
	s_add_i32 s54, s54, s2
	s_add_i32 s58, s58, s2
	v_add_u32_e32 v138, 0, v5
	v_or_b32_e32 v151, 0x100, v139
	v_or_b32_e32 v254, 0x200, v139
	v_or_b32_e32 v142, 0x300, v139
	v_add_u32_e32 v143, 0x800, v139
	v_add_u32_e32 v144, 0x900, v139
	v_add_u32_e32 v145, 0xa00, v139
	v_add_u32_e32 v146, 0xb00, v139
	s_mul_hi_i32 s46, s18, 0x30000
	s_mul_i32 s47, s18, 0x30000
	s_add_i32 s48, s38, 0xc000
	s_add_i32 s49, s38, 0xe000
	s_mov_b64 s[18:19], 0x100
	s_mov_b64 s[20:21], 0x180
	s_mov_b64 s[22:23], 0x200
	s_mov_b64 s[24:25], 0x280
	v_lshlrev_b32_e32 v136, 1, v0
	s_add_i32 s51, s50, 0x2000
	s_add_i32 s53, s52, 0x2000
	s_add_i32 s55, s54, 0x2000
	s_add_i32 s59, s58, 0x2000
	v_cmp_ne_u32_e64 s[4:5], 1, v1
	s_mov_b32 s62, s98
	s_mov_b64 s[26:27], s[30:31]
	s_barrier
	s_waitcnt vmcnt(0)
	s_branch .LBB0_933
